# proj phase: first projection GEMM's trailing prefetch pulls the second projection GEMM's first two K-tiles (same tile) instead of re-reading its own
# speedup vs baseline: 1.0046x; 1.0046x over previous
.LBB0_1070:
	s_ashr_i32 s17, s16, 31
	s_lshl_b64 s[20:21], s[16:17], 18
	s_add_u32 s20, s38, s20
	s_addc_u32 s21, s39, s21
	s_and_b64 s[22:23], s[0:1], exec
	s_cselect_b32 s17, s21, s31
	s_cselect_b32 s52, s20, s30
	s_ashr_i32 s19, s18, 31
	s_lshl_b64 s[22:23], s[18:19], 18
	s_add_u32 s22, s40, s22
	s_addc_u32 s23, s41, s23
	s_and_b64 s[34:35], s[0:1], exec
	s_cselect_b32 s19, s23, s29
	s_cselect_b32 s53, s22, s28
	s_and_b64 s[34:35], s[0:1], exec
	s_cbranch_scc1 .Lpjw_0
	s_add_u32 s52, s52, 0x1000000
	s_addc_u32 s17, s17, 0
	s_add_u32 s53, s53, 0x200000
	s_addc_u32 s19, s19, 0
.Lpjw_0:
	s_add_u32 s54, s28, 0x10000
	s_addc_u32 s55, s29, 0
	s_add_u32 s28, s30, 0x20080
	v_mov_b32_e32 v0, 0
	s_addc_u32 s29, s31, 0
	s_mov_b32 s56, -2
	v_mov_b32_e32 v1, v0
	v_mov_b32_e32 v2, v0
	v_mov_b32_e32 v3, v0
	v_mov_b32_e32 v4, v0
	v_mov_b32_e32 v5, v0
	v_mov_b32_e32 v6, v0
	v_mov_b32_e32 v7, v0
	v_mov_b32_e32 v12, v0
	v_mov_b32_e32 v13, v0
	v_mov_b32_e32 v14, v0
	v_mov_b32_e32 v15, v0
	v_mov_b32_e32 v20, v0
	v_mov_b32_e32 v21, v0
	v_mov_b32_e32 v22, v0
	v_mov_b32_e32 v23, v0
	v_mov_b32_e32 v28, v0
	v_mov_b32_e32 v29, v0
	v_mov_b32_e32 v30, v0
	v_mov_b32_e32 v31, v0
	v_mov_b32_e32 v36, v0
	v_mov_b32_e32 v37, v0
	v_mov_b32_e32 v38, v0
	v_mov_b32_e32 v39, v0
	v_mov_b32_e32 v44, v0
	v_mov_b32_e32 v45, v0
	v_mov_b32_e32 v46, v0
	v_mov_b32_e32 v47, v0
	v_mov_b32_e32 v52, v0
	v_mov_b32_e32 v53, v0
	v_mov_b32_e32 v54, v0
	v_mov_b32_e32 v55, v0
	v_mov_b32_e32 v8, v0
	v_mov_b32_e32 v9, v0
	v_mov_b32_e32 v10, v0
	v_mov_b32_e32 v11, v0
	v_mov_b32_e32 v16, v0
	v_mov_b32_e32 v17, v0
	v_mov_b32_e32 v18, v0
	v_mov_b32_e32 v19, v0
	v_mov_b32_e32 v24, v0
	v_mov_b32_e32 v25, v0
	v_mov_b32_e32 v26, v0
	v_mov_b32_e32 v27, v0
	v_mov_b32_e32 v32, v0
	v_mov_b32_e32 v33, v0
	v_mov_b32_e32 v34, v0
	v_mov_b32_e32 v35, v0
	v_mov_b32_e32 v40, v0
	v_mov_b32_e32 v41, v0
	v_mov_b32_e32 v42, v0
	v_mov_b32_e32 v43, v0
	v_mov_b32_e32 v48, v0
	v_mov_b32_e32 v49, v0
	v_mov_b32_e32 v50, v0
	v_mov_b32_e32 v51, v0
	v_mov_b32_e32 v56, v0
	v_mov_b32_e32 v57, v0
	v_mov_b32_e32 v58, v0
	v_mov_b32_e32 v59, v0
	v_mov_b32_e32 v60, v0
	v_mov_b32_e32 v61, v0
	v_mov_b32_e32 v62, v0
	v_mov_b32_e32 v63, v0
	v_mov_b32_e32 v64, v0
	v_mov_b32_e32 v65, v0
	v_mov_b32_e32 v66, v0
	v_mov_b32_e32 v67, v0
	v_mov_b32_e32 v68, v0
	v_mov_b32_e32 v69, v0
	v_mov_b32_e32 v70, v0
	v_mov_b32_e32 v71, v0
	v_mov_b32_e32 v76, v0
	v_mov_b32_e32 v77, v0
	v_mov_b32_e32 v78, v0
	v_mov_b32_e32 v79, v0
	v_mov_b32_e32 v80, v0
	v_mov_b32_e32 v81, v0
	v_mov_b32_e32 v82, v0
	v_mov_b32_e32 v83, v0
	v_mov_b32_e32 v96, v0
	v_mov_b32_e32 v97, v0
	v_mov_b32_e32 v98, v0
	v_mov_b32_e32 v99, v0
	v_mov_b32_e32 v100, v0
	v_mov_b32_e32 v101, v0
	v_mov_b32_e32 v102, v0
	v_mov_b32_e32 v103, v0
	v_mov_b32_e32 v104, v0
	v_mov_b32_e32 v105, v0
	v_mov_b32_e32 v106, v0
	v_mov_b32_e32 v107, v0
	v_mov_b32_e32 v108, v0
	v_mov_b32_e32 v109, v0
	v_mov_b32_e32 v110, v0
	v_mov_b32_e32 v111, v0
	v_mov_b32_e32 v72, v0
	v_mov_b32_e32 v73, v0
	v_mov_b32_e32 v74, v0
	v_mov_b32_e32 v75, v0
	v_mov_b32_e32 v84, v0
	v_mov_b32_e32 v85, v0
	v_mov_b32_e32 v86, v0
	v_mov_b32_e32 v87, v0
	v_mov_b32_e32 v88, v0
	v_mov_b32_e32 v89, v0
	v_mov_b32_e32 v90, v0
	v_mov_b32_e32 v91, v0
	v_mov_b32_e32 v92, v0
	v_mov_b32_e32 v93, v0
	v_mov_b32_e32 v94, v0
	v_mov_b32_e32 v95, v0
	v_mov_b32_e32 v112, v0
	v_mov_b32_e32 v113, v0
	v_mov_b32_e32 v114, v0
	v_mov_b32_e32 v115, v0
	v_mov_b32_e32 v116, v0
	v_mov_b32_e32 v117, v0
	v_mov_b32_e32 v118, v0
	v_mov_b32_e32 v119, v0
	v_mov_b32_e32 v120, v0
	v_mov_b32_e32 v121, v0
	v_mov_b32_e32 v122, v0
	v_mov_b32_e32 v123, v0
	v_mov_b32_e32 v124, v0
	v_mov_b32_e32 v125, v0
	v_mov_b32_e32 v126, v0
	v_mov_b32_e32 v127, v0
